# hyena (last layer) unit start: filter halo loads no longer awaited before the row loads are issued (upper halves of two halo loads dropped to remove the register overlap); wait moved to the consumers
# speedup vs baseline: 1.0052x; 1.0052x over previous
.LBB0_3328:
	s_or_b64 exec, exec, s[8:9]
	v_cmp_gt_u32_e32 vcc, s42, v116
	v_mov_b32_e32 v26, 0
	s_and_saveexec_b64 s[8:9], vcc
	s_cbranch_execz .LBB0_3330
	s_waitcnt vmcnt(3)
	v_ashrrev_i32_e32 v3, 31, v114
	s_waitcnt vmcnt(2)
	v_mov_b32_e32 v2, v114
	v_lshl_add_u64 v[2:3], v[2:3], 1, s[16:17]
	global_load_dwordx2 v[26:27], v[2:3], off offset:16

.LBB0_3334:
	s_or_b64 exec, exec, s[10:11]
	v_cmp_lt_u32_e32 vcc, s43, v116
	v_mov_b32_e32 v40, 0
	s_and_saveexec_b64 s[10:11], vcc
	s_cbranch_execz .LBB0_3336
	v_ashrrev_i32_e32 v47, 31, v46
	s_waitcnt vmcnt(2)
	v_lshl_add_u64 v[2:3], v[46:47], 1, s[16:17]
	global_load_dwordx2 v[40:41], v[2:3], off offset:16

.LBB0_3337:
	s_or_b64 exec, exec, s[0:1]
	v_ashrrev_i32_e32 v117, 31, v116
	s_mul_hi_i32 s1, s18, 0x4800
	s_mul_i32 s0, s18, 0x4800
	s_waitcnt vmcnt(2)
	v_lshrrev_b32_e32 v2, 21, v117
	s_lshl_b64 s[20:21], s[0:1], 1
	v_add_u32_e32 v2, v116, v2
	s_add_u32 s22, s2, s20
	v_and_b32_e32 v2, 0xfffff800, v2
	s_addc_u32 s23, s30, s21
	v_sub_u32_e32 v119, v116, v2
	v_cmp_gt_i32_e32 vcc, s48, v135
	v_mov_b32_e32 v68, 0
	v_mov_b32_e32 v67, 0
	v_mov_b32_e32 v45, 0
	v_mov_b32_e32 v44, 0
	v_mov_b32_e32 v43, 0
	v_mov_b32_e32 v42, 0
	s_and_saveexec_b64 s[10:11], vcc
	s_cbranch_execz .LBB0_3343
	v_lshl_add_u64 v[2:3], v[116:117], 1, s[22:23]
	global_load_dwordx4 v[42:45], v[2:3], off
	v_cmp_lt_i32_e64 s[0:1], 0, v119
	v_mov_b32_e32 v68, 0
	v_mov_b32_e32 v67, 0
	s_and_saveexec_b64 s[12:13], s[0:1]
	s_cbranch_execz .LBB0_3340
	global_load_ushort v67, v[2:3], off offset:-2

.LBB0_3386:
	s_waitcnt vmcnt(0)
	v_perm_b32 v23, v37, v38, s53
	v_perm_b32 v24, v38, v39, s53
	v_perm_b32 v25, v39, v40, s53
	v_perm_b32 v22, v36, v37, s53
	v_pk_mov_b32 v[72:73], v[38:39], v[40:41] op_sel:[1,0]
	v_pk_mov_b32 v[70:71], v[36:37], v[38:39] op_sel:[1,0]
	v_perm_b32 v77, v40, v41, s53
	v_mov_b32_e32 v74, v23
	v_mov_b32_e32 v75, v24
	v_mov_b32_e32 v76, v25
	ds_write_b128 v121, v[36:39] offset:8192
	ds_write_b128 v121, v[22:25] offset:16416
	ds_write_b128 v121, v[70:73] offset:24640
	ds_write_b128 v121, v[74:77] offset:32864

.LBB0_3400:
	s_waitcnt vmcnt(0)
	v_perm_b32 v71, v23, v24, s53
	v_perm_b32 v72, v24, v25, s53
	v_perm_b32 v73, v25, v26, s53
	v_perm_b32 v70, v22, v23, s53
	v_pk_mov_b32 v[76:77], v[24:25], v[26:27] op_sel:[1,0]
	v_pk_mov_b32 v[74:75], v[22:23], v[24:25] op_sel:[1,0]
	v_perm_b32 v83, v26, v27, s53
	v_mov_b32_e32 v80, v71
	v_mov_b32_e32 v81, v72
	v_mov_b32_e32 v82, v73
	ds_write_b128 v121, v[22:25]
	ds_write_b128 v121, v[70:73] offset:8224
	ds_write_b128 v121, v[74:77] offset:16448
	ds_write_b128 v121, v[80:83] offset:24672
	s_or_b64 exec, exec, s[0:1]
	s_and_saveexec_b64 s[0:1], s[8:9]
	s_cbranch_execnz .LBB0_3386
	s_branch .LBB0_3387
